# scan: dropped the three per-chunk lane counter updates that the scalar chunk offset made dead
# speedup vs baseline: 1.0109x; 1.0109x over previous
; __device__ __forceinline__ void rwkv_scan_unit(const Params& p, int unit, char* smem) {
;     ...
;         {
;             const int u = tid >> 4, r = tid & 15;
;             Yb[((size_t)b * TT + step_tok(ci * SCH + u, d)) * 1024 + r] = f2bf(*((const float*)(smem + YOFF + (ci & 1) * 1024) + u * 16 + r));
;         }
.Lsc_p0_flush:
	v_lshlrev_b32_e32 v12, 2, v73
	v_add3_u32 v12, s52, v89, v12
	s_waitcnt lgkmcnt(0)
	s_barrier
	ds_read_b32 v12, v12 offset:43008
	v_add_u32_e32 v13, s55, v71
	s_movk_i32 s0, 0x7fff
	v_cmp_lt_i32_e32 vcc, s2, v13
	s_add_i32 s55, s55, 16
	s_waitcnt lgkmcnt(0)
	v_bfe_u32 v14, v12, 16, 1
	v_add3_u32 v14, v12, v14, s0
	v_cndmask_b32_e32 v12, v196, v197, vcc
	v_add_u32_e32 v12, v12, v82
	v_cndmask_b32_e64 v12, v12, v13, s[44:45]
	v_ashrrev_i32_e32 v13, 31, v12
	v_lshl_add_u64 v[12:13], v[12:13], 0, s[88:89]
	v_lshlrev_b64 v[12:13], 11, v[12:13]
	s_add_i32 s64, s64, 1
	v_lshl_add_u64 v[12:13], v[48:49], 0, v[12:13]
	v_add_u32_e32 v82, -16, v82
	s_cmpk_lg_i32 s55, 0x1100
	global_store_short_d16_hi v[12:13], v14, off

; #define SC_LSTORE(st_) { SC_S1(st_, 0, rg0) SC_S1(st_, 1, rg1) SC_S1(st_, 2, rg2) }
; __device__ __forceinline__ void rwkv_scan_unit(const Params& p, int unit, char* smem) {
;     ...
;         if (ci + 1 < NCH) { SC_LSTORE(((ci + 1) & 1) * STG) }
;         __syncthreads();
;         {
;             const int u = tid >> 4, r = tid & 15;
;             Yb[((size_t)b * TT + step_tok(ci * SCH + u, d)) * 1024 + r] = f2bf(*((const float*)(smem + YOFF + (ci & 1) * 1024) + u * 16 + r));
;         }
.Lsc_p3_flush:
	v_lshlrev_b32_e32 v12, 2, v73
	v_add3_u32 v12, s52, v89, v12
	s_waitcnt lgkmcnt(0)
	s_barrier
	ds_read_b32 v12, v12 offset:43008
	v_add_u32_e32 v13, s55, v71
	s_movk_i32 s0, 0x7fff
	v_cmp_lt_i32_e32 vcc, s2, v13
	s_add_i32 s55, s55, 16
	s_waitcnt lgkmcnt(0)
	v_bfe_u32 v14, v12, 16, 1
	v_add3_u32 v14, v12, v14, s0
	v_cndmask_b32_e32 v12, v196, v197, vcc
	v_add_u32_e32 v12, v12, v82
	v_cndmask_b32_e64 v12, v12, v13, s[44:45]
	v_ashrrev_i32_e32 v13, 31, v12
	v_lshl_add_u64 v[12:13], v[12:13], 0, s[88:89]
	v_lshlrev_b64 v[12:13], 11, v[12:13]
	s_add_i32 s64, s64, 1
	v_lshl_add_u64 v[12:13], v[48:49], 0, v[12:13]
	v_add_u32_e32 v82, -16, v82
	s_cmpk_lg_i32 s55, 0x1100
	global_store_short_d16_hi v[12:13], v14, off
	s_cbranch_scc0 .LBB0_420
	s_branch .Lsc_p0
